# grid barrier: non-leader workgroups poll the top-level generation word directly (one polling hop less on the release path)
# speedup vs baseline: 1.0066x; 1.0066x over previous
.LBB0_67:
	s_or_b64 exec, exec, s[6:7]
	v_cvt_f32_u32_e32 v5, v3
	s_waitcnt vmcnt(0)
	v_readfirstlane_b32 s0, v4
	v_sub_u32_e32 v4, 0, v3
	v_rcp_iflag_f32_e32 v5, v5
	v_add_u32_e32 v6, s0, v2
	v_mul_f32_e32 v5, 0x4f7ffffe, v5
	v_cvt_u32_f32_e32 v5, v5
	v_mul_lo_u32 v2, v4, v5
	v_mul_hi_u32 v2, v5, v2
	v_add_u32_e32 v2, v5, v2
	v_mul_hi_u32 v2, v6, v2
	v_mul_lo_u32 v4, v2, v3
	v_sub_u32_e32 v4, v6, v4
	v_add_u32_e32 v5, 1, v2
	v_cmp_ge_u32_e32 vcc, v4, v3
	s_nop 1
	v_cndmask_b32_e32 v2, v2, v5, vcc
	v_sub_u32_e32 v5, v4, v3
	v_cndmask_b32_e32 v4, v4, v5, vcc
	v_add_u32_e32 v5, 1, v2
	v_cmp_ge_u32_e32 vcc, v4, v3
	v_add_u32_e32 v4, 1, v6
	s_nop 0
	v_cndmask_b32_e32 v2, v2, v5, vcc
	v_mul_lo_u32 v5, v3, v2
	v_add_u32_e32 v3, v5, v3
	v_cmp_ne_u32_e32 vcc, v4, v3
	s_and_saveexec_b64 s[0:1], vcc
	s_xor_b64 s[6:7], exec, s[0:1]
	s_cbranch_execz .LBB0_81
	v_readlane_b32 s0, v249, 61
	s_waitcnt lgkmcnt(0)
	v_mov_b32_e32 v1, 0
	v_readlane_b32 s1, v249, 62
	s_nop 4
	global_load_dword v3, v1, s[0:1] sc1
	s_waitcnt vmcnt(0)
	v_cmp_eq_u32_e32 vcc, v3, v2
	s_and_saveexec_b64 s[8:9], vcc
	s_cbranch_execz .LBB0_80
	s_mov_b32 s0, 1
	s_mov_b64 s[10:11], 0
	s_branch .LBB0_71

.LBB0_75:
	v_readlane_b32 s2, v249, 61
	v_readlane_b32 s3, v249, 62
	s_add_i32 s0, s0, 1
	s_mov_b64 s[16:17], -1
	s_nop 2
	global_load_dword v3, v1, s[2:3] sc1
	s_waitcnt vmcnt(0)
	v_cmp_ne_u32_e32 vcc, v3, v2
	s_orn2_b64 s[14:15], vcc, exec
	s_branch .LBB0_70

.LBB0_144:
	s_or_b64 exec, exec, s[8:9]
	v_cvt_f32_u32_e32 v6, v4
	s_waitcnt vmcnt(0)
	v_readfirstlane_b32 s4, v5
	v_sub_u32_e32 v5, 0, v4
	v_rcp_iflag_f32_e32 v6, v6
	v_add_u32_e32 v7, s4, v3
	v_mul_f32_e32 v6, 0x4f7ffffe, v6
	v_cvt_u32_f32_e32 v6, v6
	v_mul_lo_u32 v3, v5, v6
	v_mul_hi_u32 v3, v6, v3
	v_add_u32_e32 v3, v6, v3
	v_mul_hi_u32 v3, v7, v3
	v_mul_lo_u32 v5, v3, v4
	v_sub_u32_e32 v5, v7, v5
	v_add_u32_e32 v6, 1, v3
	v_cmp_ge_u32_e32 vcc, v5, v4
	s_nop 1
	v_cndmask_b32_e32 v3, v3, v6, vcc
	v_sub_u32_e32 v6, v5, v4
	v_cndmask_b32_e32 v5, v5, v6, vcc
	v_add_u32_e32 v6, 1, v3
	v_cmp_ge_u32_e32 vcc, v5, v4
	v_add_u32_e32 v5, 1, v7
	s_nop 0
	v_cndmask_b32_e32 v3, v3, v6, vcc
	v_mul_lo_u32 v6, v4, v3
	v_add_u32_e32 v4, v6, v4
	v_cmp_ne_u32_e32 vcc, v5, v4
	s_and_saveexec_b64 s[8:9], vcc
	s_xor_b64 s[8:9], exec, s[8:9]
	s_cbranch_execz .LBB0_158
	v_readlane_b32 s10, v249, 61
	v_readlane_b32 s11, v249, 62
	s_waitcnt lgkmcnt(0)
	s_nop 3
	global_load_dword v2, v67, s[10:11] sc1
	s_waitcnt vmcnt(0)
	v_cmp_eq_u32_e32 vcc, v2, v3
	s_and_saveexec_b64 s[10:11], vcc
	s_cbranch_execz .LBB0_157
	s_mov_b32 s4, 1
	s_mov_b64 s[12:13], 0
	s_branch .LBB0_148

.LBB0_152:
	v_readlane_b32 s16, v249, 61
	v_readlane_b32 s17, v249, 62
	s_add_i32 s4, s4, 1
	s_mov_b64 s[18:19], -1
	s_nop 2
	global_load_dword v2, v67, s[16:17] sc1
	s_waitcnt vmcnt(0)
	v_cmp_ne_u32_e32 vcc, v2, v3
	s_orn2_b64 s[16:17], vcc, exec
	s_branch .LBB0_147

.LBB0_438:
	s_or_b64 exec, exec, s[6:7]
	v_cvt_f32_u32_e32 v6, v4
	s_waitcnt vmcnt(0)
	v_readfirstlane_b32 s6, v5
	v_sub_u32_e32 v5, 0, v4
	v_rcp_iflag_f32_e32 v6, v6
	v_add_u32_e32 v7, s6, v3
	v_mul_f32_e32 v6, 0x4f7ffffe, v6
	v_cvt_u32_f32_e32 v6, v6
	v_mul_lo_u32 v3, v5, v6
	v_mul_hi_u32 v3, v6, v3
	v_add_u32_e32 v3, v6, v3
	v_mul_hi_u32 v3, v7, v3
	v_mul_lo_u32 v5, v3, v4
	v_sub_u32_e32 v5, v7, v5
	v_add_u32_e32 v6, 1, v3
	v_cmp_ge_u32_e32 vcc, v5, v4
	s_nop 1
	v_cndmask_b32_e32 v3, v3, v6, vcc
	v_sub_u32_e32 v6, v5, v4
	v_cndmask_b32_e32 v5, v5, v6, vcc
	v_add_u32_e32 v6, 1, v3
	v_cmp_ge_u32_e32 vcc, v5, v4
	v_add_u32_e32 v5, 1, v7
	s_nop 0
	v_cndmask_b32_e32 v3, v3, v6, vcc
	v_mul_lo_u32 v6, v4, v3
	v_add_u32_e32 v4, v6, v4
	v_cmp_ne_u32_e32 vcc, v5, v4
	s_and_saveexec_b64 s[6:7], vcc
	s_xor_b64 s[6:7], exec, s[6:7]
	s_cbranch_execz .LBB0_452
	v_readlane_b32 s8, v249, 61
	v_readlane_b32 s9, v249, 62
	s_waitcnt lgkmcnt(0)
	s_nop 3
	global_load_dword v2, v203, s[8:9] sc1
	s_waitcnt vmcnt(0)
	v_cmp_eq_u32_e32 vcc, v2, v3
	s_and_saveexec_b64 s[8:9], vcc
	s_cbranch_execz .LBB0_451
	s_mov_b32 s12, 1
	s_mov_b64 s[10:11], 0
	s_branch .LBB0_442

.LBB0_446:
	v_readlane_b32 s16, v249, 61
	v_readlane_b32 s17, v249, 62
	s_add_i32 s12, s12, 1
	s_mov_b64 s[18:19], -1
	s_nop 2
	global_load_dword v2, v203, s[16:17] sc1
	s_waitcnt vmcnt(0)
	v_cmp_ne_u32_e32 vcc, v2, v3
	s_orn2_b64 s[16:17], vcc, exec
	s_branch .LBB0_441
